# cvhost group version, lean slot: per-wave LDS/lane constants kept in registers, wave row block folded into the table pointers
# speedup vs baseline: 1.0061x; 1.0061x over previous
; __device__ __forceinline__ P0Desc p0_desc(int r, int lane, const P0Ptrs& a) {
;     const int kk = lane >> 3, n4 = (lane & 7) * 4; P0Desc d; d.gs = 1.f;
;     int kb, n, sc, nsrc, ldt; const float* W; bf16_t* WT; const float* ks;
;     if (r < F_O) { kb = r >> 6; n = 32 * (r & 63) + n4; sc = n; W = a.w_o; nsrc = 2048; WT = a.WoT; ldt = 2048; ks = (kb < 16) ? a.on_a : (a.on_c - 1024); }
;     else if ((r -= F_O) < F_UP) { kb = r / 352; n = 32 * (r % 352) + n4; sc = ((n >> 7) & 1) * DFF + (n >> 8) * 128 + (n & 127); W = a.w_up; nsrc = 2 * DFF; WT = a.WupT; ldt = 2048; ks = a.ffn_g; }
;     else if ((r -= F_UP) < F_DN) { kb = r >> 6; n = 32 * (r & 63) + n4; sc = n; W = a.w_dn; nsrc = 2048; WT = a.WdT; ldt = DFF; ks = nullptr; }
;     else if ((r -= F_DN) < F_IN) { kb = r >> 7; n = 32 * (r & 127) + n4;
;         if (n < 1024) sc = n; else if (n < 2048) sc = n + 64; else sc = (((n >> 7) & 1) ? 3136 : 2112) + 128 * ((n - 2048) >> 8) + (n & 127);
;         W = a.w_in; nsrc = INW; WT = a.WinT; ldt = 2048; ks = a.attn_g; }
;     else if ((r -= F_IN) < F_Q) { kb = r >> 5; n = 32 * (6 * ((r & 31) >> 2) + (r & 3)) + n4; sc = n; W = a.w_qb; nsrc = 1536; WT = a.WqT; ldt = 2048; ks = a.qa_g; d.gs = QSCALE; }
;     else { r -= F_Q; kb = r >> 6; n = 32 * (r & 63) + n4; sc = n; W = a.w_kvb; nsrc = 2048; WT = a.WkvT; ldt = 2048; ks = a.kva_g; }
;     const int k0 = 64 * kb + 8 * kk;
;     d.src = W + (size_t)k0 * nsrc + sc; d.nsrc = nsrc; d.dst = WT + (size_t)n * ldt + k0; d.ldt = ldt; d.ks = ks ? ks + k0 : nullptr;
;     return d;
; }
; __device__ __forceinline__ int p0_super(int s, int q) {
;     int base, nbw;
;     if (s < F_O / 4) { base = 0; nbw = 64; }
;     else if ((s -= F_O / 4) < F_UP / 4) { base = F_O; nbw = 352; }
;     else if ((s -= F_UP / 4) < F_DN / 4) { base = F_O + F_UP; nbw = 64; }
;     else if ((s -= F_DN / 4) < F_IN / 4) { base = F_O + F_UP + F_DN; nbw = 128; }
;     else if ((s -= F_IN / 4) < F_Q / 4) { base = F_O + F_UP + F_DN + F_IN; nbw = 32; }
;     else { s -= F_Q / 4; base = F_O + F_UP + F_DN + F_IN + F_Q; nbw = 64; }
;     return base + ((s / nbw) * 4 + q) * nbw + (s % nbw);
; }
; template <int NB>
; __device__ __forceinline__ void p0_batch(int it0, int stride, int lane, const P0Ptrs& a) {
;     f32x4 v[NB][8], s0[NB], s1[NB]; P0Desc d[NB];
; #pragma unroll
.LBB0_759:
	v_lshl_add_u64 v[112:113], s[28:29], 0, v[146:147]
	s_mov_b64 s[54:55], 0x18fc0000
	s_mov_b32 m0, s78
	v_lshl_add_u64 v[100:101], v[112:113], 0, s[54:55]
	s_waitcnt vmcnt(0)
	s_barrier
	global_load_lds_dwordx4 v[100:101], off
	v_lshl_add_u64 v[100:101], v[112:113], 0, s[38:39]
	s_add_i32 m0, s78, 0x2000
	v_lshl_add_u64 v[136:137], s[28:29], 0, v[144:145]
	global_load_lds_dwordx4 v[100:101], off
	v_lshl_add_u64 v[100:101], v[136:137], 0, s[40:41]
	s_add_i32 m0, s78, 0x4000
	v_lshl_add_u64 v[134:135], s[28:29], 0, v[148:149]
	global_load_lds_dwordx4 v[100:101], off
	v_lshl_add_u64 v[100:101], v[134:135], 0, s[42:43]
	s_mov_b32 m0, s58
	global_load_lds_dwordx4 v[100:101], off
	v_lshl_add_u64 v[100:101], v[134:135], 0, s[44:45]
	s_mov_b32 m0, s77
	global_load_lds_dwordx4 v[100:101], off
	s_cmp_eq_u32 s87, 0
	s_cbranch_scc1 .Lg_nocons
	s_cmp_gt_u32 s32, s75
	s_cbranch_scc1 .Lg_nocons
	s_mov_b64 s[92:93], s[82:83]
	s_mov_b32 s91, s84
	s_cmp_lg_u32 s85, 0
	s_cbranch_scc1 .Lg_nomul
	v_mul_f32_e32 v238, v250, v238
	v_mul_f32_e32 v239, v250, v239
	v_mul_f32_e32 v240, v250, v240
	v_mul_f32_e32 v241, v250, v241
	v_mul_f32_e32 v242, v251, v242
	v_mul_f32_e32 v243, v251, v243
	v_mul_f32_e32 v244, v251, v244
	v_mul_f32_e32 v245, v251, v245
.Lg_nomul:
	v_cvt_pk_bf16_f32 v100, v238, v242
	v_cvt_pk_bf16_f32 v101, v239, v243
	v_cvt_pk_bf16_f32 v102, v240, v244
	v_cvt_pk_bf16_f32 v103, v241, v245
	ds_write_b32 v252, v100
	ds_write_b32 v252, v101 offset:144
	ds_write_b32 v252, v102 offset:288
	ds_write_b32 v252, v103 offset:432
	s_waitcnt lgkmcnt(0)
.Lg_nocons:
	s_cmp_eq_u32 s87, 0
	s_cbranch_scc1 .Lg_first
	s_cmp_ge_u32 s32, s75
	s_cbranch_scc1 .Lg_inc
	s_cmp_eq_u32 s32, 2
	s_cbranch_scc1 .Lg_ptr
	s_cmp_eq_u32 s32, 4
	s_cbranch_scc1 .Lg_ptr
	s_cmp_lg_u32 s32, 26
	s_cbranch_scc1 .Lg_noptr
	s_branch .Lg_ptr
.Lg_first:
	v_readfirstlane_b32 s98, v0
	s_lshr_b32 s75, s2, 8
	s_mul_i32 s75, s75, 18
	s_add_i32 s75, s75, 19
	s_and_b32 s72, s2, 0xff
	s_lshl_b32 s72, s72, 1
	s_lshr_b32 s98, s98, 6
	s_and_b32 s73, s98, 3
	s_lshl_b32 s73, s73, 3
	s_lshr_b32 s99, s98, 2
	s_or_b32 s72, s72, s99
	s_cmp_lt_u32 s98, 4
	s_mov_b32 s98, 0x26400
	s_cselect_b32 s98, 0x1e800, s98
	v_and_b32_e32 v76, 63, v0
	v_lshrrev_b32_e32 v77, 3, v76
	v_and_b32_e32 v78, 7, v76
	s_lshl_b32 s99, s73, 2
	s_add_i32 s99, s99, s98
	v_mul_u32_u24_e32 v252, 0x240, v78
	v_lshl_add_u32 v252, v77, 2, v252
	v_add_u32_e32 v252, s99, v252
	s_mul_i32 s99, s73, 0x90
	s_add_i32 s99, s99, s98
	v_mul_u32_u24_e32 v253, 0x90, v77
	v_lshl_add_u32 v253, v78, 4, v253
	v_add_u32_e32 v253, s99, v253
	v_lshlrev_b32_e32 v255, 3, v77
.Lg_ptr:
	s_movk_i32 s98, 0x78
	s_cmp_lt_u32 s32, 26
	s_cselect_b32 s98, 0x60, s98
	s_cmp_lt_u32 s32, 4
	s_cselect_b32 s98, 0x50, s98
	s_movk_i32 s99, 0x58
	s_cselect_b32 s99, 0x48, s99
	s_cmp_lt_u32 s32, 2
	s_cselect_b32 s99, 64, s99
	s_load_dwordx2 s[88:89], s[100:101], s98
	s_load_dwordx2 s[94:95], s[100:101], s99
	s_waitcnt lgkmcnt(0)
	s_mov_b32 s90, 0x2000
	s_add_i32 s98, s32, -4
	s_cmp_lt_u32 s98, 22
	s_cselect_b32 s90, 0xb000, s90
	s_mov_b32 s99, 0x1000
	s_cmp_lt_u32 s32, 26
	s_cselect_b32 s99, s99, 0x2c00
	s_lshl_b32 s98, s73, 1
	s_mul_i32 s98, s98, s90
	s_add_u32 s88, s88, s98
	s_addc_u32 s89, s89, 0
	s_lshl_b32 s98, s73, 3
	s_add_u32 s94, s94, s98
	s_addc_u32 s95, s95, 0
	v_and_b32_e32 v76, 63, v0
	v_lshrrev_b32_e32 v77, 3, v76
	v_and_b32_e32 v78, 7, v76
	v_lshlrev_b32_e32 v78, 4, v78
	s_lshl_b32 s98, s90, 1
	v_mad_u32_u24 v254, v77, s98, v78
.Lg_noptr:
	s_cmp_lt_u32 s32, 4
	s_cbranch_scc1 .Lg_t0
	s_cmp_lt_u32 s32, 26
	s_cbranch_scc1 .Lg_t1
	s_add_i32 s98, s32, -26
	s_lshl_b32 s98, s98, 9
	s_add_i32 s98, s98, s72
	s_lshr_b32 s74, s98, 6
	s_and_b32 s86, s98, 63
	s_mov_b32 s84, 0x2c00
	s_mov_b32 s85, 1
	s_lshl_b32 s98, s74, 19
	s_lshl_b32 s99, s86, 7
	s_add_i32 s98, s98, s99
	s_mul_i32 s99, s86, 0x58000
	s_lshl_b32 s82, s74, 7
	s_add_i32 s99, s99, s82
	s_add_i32 s99, s99, 0x6900000
	s_mov_b32 s74, 0
	s_branch .Lg_tdone
.Lg_t1:
	s_add_i32 s98, s32, -4
	s_lshl_b32 s98, s98, 9
	s_add_i32 s98, s98, s72
	s_mul_hi_u32 s74, s98, 0xba2e8c
	s_mul_i32 s99, s74, 0x160
	s_sub_i32 s86, s98, s99
	s_mov_b32 s84, 0x1000
	s_mov_b32 s85, 0
	s_bfe_u32 s98, s86, 0x10002
	s_mul_i32 s98, s98, 0x5800
	s_lshr_b32 s99, s86, 3
	s_lshl_b32 s99, s99, 9
	s_add_i32 s98, s98, s99
	s_and_b32 s99, s86, 3
	s_lshl_b32 s99, s99, 7
	s_add_i32 s98, s98, s99
	s_mul_i32 s99, s74, 0x2c0000
	s_add_i32 s98, s98, s99
	s_lshl_b32 s99, s86, 17
	s_lshl_b32 s82, s74, 7
	s_add_i32 s99, s99, s82
	s_add_i32 s99, s99, 0x3d00000
	s_lshl_b32 s74, s74, 8
	s_branch .Lg_tdone
.Lg_t0:
	s_lshl_b32 s98, s32, 9
	s_add_i32 s98, s98, s72
	s_lshr_b32 s74, s98, 6
	s_and_b32 s86, s98, 63
	s_mov_b32 s84, 0x1000
	s_mov_b32 s85, 0
	s_lshl_b32 s98, s74, 19
	s_lshl_b32 s99, s86, 7
	s_add_i32 s98, s98, s99
	s_lshl_b32 s99, s86, 17
	s_lshl_b32 s82, s74, 7
	s_add_i32 s99, s99, s82
	s_add_i32 s99, s99, 0x3500000
	s_lshl_b32 s82, s74, 8
	s_cmp_lt_u32 s74, 16
	s_cselect_b32 s74, 0, 0x1000
	s_sub_i32 s74, s82, s74
.Lg_tdone:
	s_add_u32 s82, s28, s99
	s_addc_u32 s83, s29, 0
	s_add_u32 s98, s88, s98
	s_addc_u32 s99, s89, 0
	global_load_dwordx4 v[238:241], v254, s[98:99] nt
	s_add_u32 s98, s98, s90
	s_addc_u32 s99, s99, 0
	global_load_dwordx4 v[242:245], v254, s[98:99] nt
	s_add_u32 s98, s94, s74
	s_addc_u32 s99, s95, 0
	global_load_dwordx2 v[250:251], v255, s[98:99]

.LBB0_764:
	s_cmp_le_u32 s32, s75
	s_cbranch_scc1 .Lg_w3
	s_waitcnt vmcnt(0)
	s_branch .Lg_wd

; #define GAS __attribute__((address_space(1)))
; __device__ __forceinline__ unsigned cvt_pk_bf16(float lo, float hi) { unsigned r; asm volatile("v_cvt_pk_bf16_f32 %0, %1, %2" : "=v"(r) : "v"(lo), "v"(hi)); return r; }
; template <int NB>
; __device__ __forceinline__ void p0_batch(int it0, int stride, int lane, const P0Ptrs& a) {
;     ...
;         if (d[q].dst) {
; #pragma unroll
;             for (int e = 0; e < 4; ++e) { u32x4 o; o.x = cvt_pk_bf16(v[q][0][e], v[q][1][e]); o.y = cvt_pk_bf16(v[q][2][e], v[q][3][e]); o.z = cvt_pk_bf16(v[q][4][e], v[q][5][e]); o.w = cvt_pk_bf16(v[q][6][e], v[q][7][e]);
;                 *(GAS u32x4*)(d[q].dst + (size_t)e * d[q].ldt) = o; } }
;     }
.LBB0_766:
	s_cmp_lt_u32 s87, 2
	s_cbranch_scc1 .Lg_bdone
	s_add_i32 s98, s75, 1
	s_cmp_gt_u32 s32, s98
	s_cbranch_scc1 .Lg_bdone
	ds_read_b128 v[100:103], v253
	v_and_b32_e32 v84, 63, v0
	v_lshrrev_b32_e32 v85, 3, v84
	v_and_b32_e32 v86, 7, v84
	v_lshlrev_b32_e32 v86, 4, v86
	v_mad_u32_u24 v88, v85, s91, v86
	s_mul_i32 s99, s73, s91
	s_add_u32 s98, s92, s99
	s_addc_u32 s99, s93, 0
	s_waitcnt lgkmcnt(0)
	global_store_dwordx4 v88, v[100:103], s[98:99]
